# ffn2 epilogue: residual loads without the non-temporal hint (the rows were written two phases earlier and may still be cached)
# speedup vs baseline: 1.0006x; 1.0006x over previous
;     __device__ __forceinline__ void operator()(const f32x4 (&acc)[2][2][4][2], const Unit& u, int wr, int wc, int fr, int fq) const {
;         const int col0 = u.pn * BM + wc * 32 + 8 * fq;
; #pragma unroll
;         for (int ai = 0; ai < 2; ++ai)
; #pragma unroll
;             for (int m = 0; m < 4; ++m) {
;                 const size_t off = (size_t)(u.pm * BM + ai * HALF + wr * 64 + m * 16 + fr) * 1024 + col0;
; #pragma unroll
;                 for (int bj = 0; bj < 2; ++bj) {
;                     f32x4 b0, b1; unpack8(__builtin_nontemporal_load((const u32x4*)(base + off + bj * HALF)), b0, b1);
;                     __builtin_nontemporal_store(b0 + acc[ai][bj][m][0], (f32x4*)(out + off + bj * HALF));
;                     __builtin_nontemporal_store(b1 + acc[ai][bj][m][1], (f32x4*)(out + off + bj * HALF + 4));
;                 }
.LBB0_2275:
	v_lshl_add_u32 v142, s47, 8, v144
	v_lshl_add_u32 v140, s48, 8, v146
	v_ashrrev_i32_e32 v141, 31, v140
	s_andn2_b64 vcc, exec, s[0:1]
	s_mov_b64 s[0:1], -1
	v_mov_b32_e32 v228, v142
	v_ashrrev_i32_e32 v229, 31, v228
	v_lshlrev_b64 v[228:229], 10, v[228:229]
	v_lshl_add_u64 v[228:229], v[228:229], 0, v[140:141]
	v_lshl_add_u64 v[230:231], v[228:229], 1, s[4:5]
	global_load_dwordx4 v[160:163], v[230:231], off
	global_load_dwordx4 v[164:167], v[230:231], off offset:256
	v_or_b32_e32 v228, 16, v142
	v_ashrrev_i32_e32 v229, 31, v228
	v_lshlrev_b64 v[228:229], 10, v[228:229]
	v_lshl_add_u64 v[228:229], v[228:229], 0, v[140:141]
	v_lshl_add_u64 v[230:231], v[228:229], 1, s[4:5]
	global_load_dwordx4 v[168:171], v[230:231], off
	global_load_dwordx4 v[172:175], v[230:231], off offset:256
	v_or_b32_e32 v228, 32, v142
	v_ashrrev_i32_e32 v229, 31, v228
	v_lshlrev_b64 v[228:229], 10, v[228:229]
	v_lshl_add_u64 v[228:229], v[228:229], 0, v[140:141]
	v_lshl_add_u64 v[230:231], v[228:229], 1, s[4:5]
	global_load_dwordx4 v[176:179], v[230:231], off
	global_load_dwordx4 v[180:183], v[230:231], off offset:256
	v_or_b32_e32 v228, 48, v142
	v_ashrrev_i32_e32 v229, 31, v228
	v_lshlrev_b64 v[228:229], 10, v[228:229]
	v_lshl_add_u64 v[228:229], v[228:229], 0, v[140:141]
	v_lshl_add_u64 v[230:231], v[228:229], 1, s[4:5]
	global_load_dwordx4 v[184:187], v[230:231], off
	global_load_dwordx4 v[188:191], v[230:231], off offset:256
	v_add_u32_e32 v228, 0x80, v142
	v_ashrrev_i32_e32 v229, 31, v228
	v_lshlrev_b64 v[228:229], 10, v[228:229]
	v_lshl_add_u64 v[228:229], v[228:229], 0, v[140:141]
	v_lshl_add_u64 v[230:231], v[228:229], 1, s[4:5]
	global_load_dwordx4 v[192:195], v[230:231], off
	global_load_dwordx4 v[196:199], v[230:231], off offset:256
	v_add_u32_e32 v228, 0x90, v142
	v_ashrrev_i32_e32 v229, 31, v228
	v_lshlrev_b64 v[228:229], 10, v[228:229]
	v_lshl_add_u64 v[228:229], v[228:229], 0, v[140:141]
	v_lshl_add_u64 v[230:231], v[228:229], 1, s[4:5]
	global_load_dwordx4 v[200:203], v[230:231], off
	global_load_dwordx4 v[204:207], v[230:231], off offset:256
	v_add_u32_e32 v228, 0xa0, v142
	v_ashrrev_i32_e32 v229, 31, v228
	v_lshlrev_b64 v[228:229], 10, v[228:229]
	v_lshl_add_u64 v[228:229], v[228:229], 0, v[140:141]
	v_lshl_add_u64 v[230:231], v[228:229], 1, s[4:5]
	global_load_dwordx4 v[208:211], v[230:231], off
	global_load_dwordx4 v[212:215], v[230:231], off offset:256
	v_add_u32_e32 v228, 0xb0, v142
	v_ashrrev_i32_e32 v229, 31, v228
	v_lshlrev_b64 v[228:229], 10, v[228:229]
	v_lshl_add_u64 v[228:229], v[228:229], 0, v[140:141]
	v_lshl_add_u64 v[230:231], v[228:229], 1, s[4:5]
	global_load_dwordx4 v[216:219], v[230:231], off
	global_load_dwordx4 v[220:223], v[230:231], off offset:256
	s_waitcnt vmcnt(15)
	v_lshlrev_b32_e32 v232, 16, v160
	v_and_b32_e32 v233, 0xffff0000, v160
	v_lshlrev_b32_e32 v234, 16, v161
	v_and_b32_e32 v235, 0xffff0000, v161
	v_lshlrev_b32_e32 v236, 16, v162
	v_and_b32_e32 v237, 0xffff0000, v162
	v_lshlrev_b32_e32 v238, 16, v163
	v_and_b32_e32 v239, 0xffff0000, v163
	v_pk_add_f32 v[124:125], v[124:125], v[232:233]
	v_pk_add_f32 v[126:127], v[126:127], v[234:235]
	v_pk_add_f32 v[120:121], v[120:121], v[236:237]
	v_pk_add_f32 v[122:123], v[122:123], v[238:239]
	s_waitcnt vmcnt(14)
	v_lshlrev_b32_e32 v232, 16, v164
	v_and_b32_e32 v233, 0xffff0000, v164
	v_lshlrev_b32_e32 v234, 16, v165
	v_and_b32_e32 v235, 0xffff0000, v165
	v_lshlrev_b32_e32 v236, 16, v166
	v_and_b32_e32 v237, 0xffff0000, v166
	v_lshlrev_b32_e32 v238, 16, v167
	v_and_b32_e32 v239, 0xffff0000, v167
	v_pk_add_f32 v[116:117], v[116:117], v[232:233]
	v_pk_add_f32 v[118:119], v[118:119], v[234:235]
	v_pk_add_f32 v[112:113], v[112:113], v[236:237]
	v_pk_add_f32 v[114:115], v[114:115], v[238:239]
	s_waitcnt vmcnt(13)
	v_lshlrev_b32_e32 v232, 16, v168
	v_and_b32_e32 v233, 0xffff0000, v168
	v_lshlrev_b32_e32 v234, 16, v169
	v_and_b32_e32 v235, 0xffff0000, v169
	v_lshlrev_b32_e32 v236, 16, v170
	v_and_b32_e32 v237, 0xffff0000, v170
	v_lshlrev_b32_e32 v238, 16, v171
	v_and_b32_e32 v239, 0xffff0000, v171
	v_pk_add_f32 v[108:109], v[108:109], v[232:233]
	v_pk_add_f32 v[110:111], v[110:111], v[234:235]
	v_pk_add_f32 v[104:105], v[104:105], v[236:237]
	v_pk_add_f32 v[106:107], v[106:107], v[238:239]
	s_waitcnt vmcnt(12)
	v_lshlrev_b32_e32 v232, 16, v172
	v_and_b32_e32 v233, 0xffff0000, v172
	v_lshlrev_b32_e32 v234, 16, v173
	v_and_b32_e32 v235, 0xffff0000, v173
	v_lshlrev_b32_e32 v236, 16, v174
	v_and_b32_e32 v237, 0xffff0000, v174
	v_lshlrev_b32_e32 v238, 16, v175
	v_and_b32_e32 v239, 0xffff0000, v175
	v_pk_add_f32 v[100:101], v[100:101], v[232:233]
	v_pk_add_f32 v[102:103], v[102:103], v[234:235]
	v_pk_add_f32 v[96:97], v[96:97], v[236:237]
	v_pk_add_f32 v[98:99], v[98:99], v[238:239]
	s_waitcnt vmcnt(11)
	v_lshlrev_b32_e32 v232, 16, v176
	v_and_b32_e32 v233, 0xffff0000, v176
	v_lshlrev_b32_e32 v234, 16, v177
	v_and_b32_e32 v235, 0xffff0000, v177
	v_lshlrev_b32_e32 v236, 16, v178
	v_and_b32_e32 v237, 0xffff0000, v178
	v_lshlrev_b32_e32 v238, 16, v179
	v_and_b32_e32 v239, 0xffff0000, v179
	v_pk_add_f32 v[92:93], v[92:93], v[232:233]
	v_pk_add_f32 v[94:95], v[94:95], v[234:235]
	v_pk_add_f32 v[88:89], v[88:89], v[236:237]
	v_pk_add_f32 v[90:91], v[90:91], v[238:239]
	s_waitcnt vmcnt(10)
	v_lshlrev_b32_e32 v232, 16, v180
	v_and_b32_e32 v233, 0xffff0000, v180
	v_lshlrev_b32_e32 v234, 16, v181
	v_and_b32_e32 v235, 0xffff0000, v181
	v_lshlrev_b32_e32 v236, 16, v182
	v_and_b32_e32 v237, 0xffff0000, v182
	v_lshlrev_b32_e32 v238, 16, v183
	v_and_b32_e32 v239, 0xffff0000, v183
	v_pk_add_f32 v[84:85], v[84:85], v[232:233]
	v_pk_add_f32 v[86:87], v[86:87], v[234:235]
	v_pk_add_f32 v[80:81], v[80:81], v[236:237]
	v_pk_add_f32 v[82:83], v[82:83], v[238:239]
	s_waitcnt vmcnt(9)
;     __device__ __forceinline__ void operator()(const f32x4 (&acc)[2][2][4][2], const Unit& u, int wr, int wc, int fr, int fq) const {
;     ...
;                 for (int bj = 0; bj < 2; ++bj) {
;                     f32x4 b0, b1; unpack8(__builtin_nontemporal_load((const u32x4*)(base + off + bj * HALF)), b0, b1);
;                     __builtin_nontemporal_store(b0 + acc[ai][bj][m][0], (f32x4*)(out + off + bj * HALF));
;                     __builtin_nontemporal_store(b1 + acc[ai][bj][m][1], (f32x4*)(out + off + bj * HALF + 4));
	v_lshlrev_b32_e32 v232, 16, v184
	v_and_b32_e32 v233, 0xffff0000, v184
	v_lshlrev_b32_e32 v234, 16, v185
	v_and_b32_e32 v235, 0xffff0000, v185
	v_lshlrev_b32_e32 v236, 16, v186
	v_and_b32_e32 v237, 0xffff0000, v186
	v_lshlrev_b32_e32 v238, 16, v187
	v_and_b32_e32 v239, 0xffff0000, v187
	v_pk_add_f32 v[76:77], v[76:77], v[232:233]
	v_pk_add_f32 v[78:79], v[78:79], v[234:235]
	v_pk_add_f32 v[72:73], v[72:73], v[236:237]
	v_pk_add_f32 v[74:75], v[74:75], v[238:239]
	s_waitcnt vmcnt(8)
	v_lshlrev_b32_e32 v232, 16, v188
	v_and_b32_e32 v233, 0xffff0000, v188
	v_lshlrev_b32_e32 v234, 16, v189
	v_and_b32_e32 v235, 0xffff0000, v189
	v_lshlrev_b32_e32 v236, 16, v190
	v_and_b32_e32 v237, 0xffff0000, v190
	v_lshlrev_b32_e32 v238, 16, v191
	v_and_b32_e32 v239, 0xffff0000, v191
	v_pk_add_f32 v[68:69], v[68:69], v[232:233]
	v_pk_add_f32 v[70:71], v[70:71], v[234:235]
	v_pk_add_f32 v[64:65], v[64:65], v[236:237]
	v_pk_add_f32 v[66:67], v[66:67], v[238:239]
	s_waitcnt vmcnt(7)
	v_lshlrev_b32_e32 v232, 16, v192
	v_and_b32_e32 v233, 0xffff0000, v192
	v_lshlrev_b32_e32 v234, 16, v193
	v_and_b32_e32 v235, 0xffff0000, v193
	v_lshlrev_b32_e32 v236, 16, v194
	v_and_b32_e32 v237, 0xffff0000, v194
	v_lshlrev_b32_e32 v238, 16, v195
	v_and_b32_e32 v239, 0xffff0000, v195
	v_pk_add_f32 v[60:61], v[60:61], v[232:233]
	v_pk_add_f32 v[62:63], v[62:63], v[234:235]
	v_pk_add_f32 v[56:57], v[56:57], v[236:237]
	v_pk_add_f32 v[58:59], v[58:59], v[238:239]
	s_waitcnt vmcnt(6)
	v_lshlrev_b32_e32 v232, 16, v196
	v_and_b32_e32 v233, 0xffff0000, v196
	v_lshlrev_b32_e32 v234, 16, v197
	v_and_b32_e32 v235, 0xffff0000, v197
	v_lshlrev_b32_e32 v236, 16, v198
	v_and_b32_e32 v237, 0xffff0000, v198
	v_lshlrev_b32_e32 v238, 16, v199
	v_and_b32_e32 v239, 0xffff0000, v199
	v_pk_add_f32 v[52:53], v[52:53], v[232:233]
	v_pk_add_f32 v[54:55], v[54:55], v[234:235]
	v_pk_add_f32 v[48:49], v[48:49], v[236:237]
	v_pk_add_f32 v[50:51], v[50:51], v[238:239]
	s_waitcnt vmcnt(5)
	v_lshlrev_b32_e32 v232, 16, v200
	v_and_b32_e32 v233, 0xffff0000, v200
	v_lshlrev_b32_e32 v234, 16, v201
	v_and_b32_e32 v235, 0xffff0000, v201
	v_lshlrev_b32_e32 v236, 16, v202
	v_and_b32_e32 v237, 0xffff0000, v202
	v_lshlrev_b32_e32 v238, 16, v203
	v_and_b32_e32 v239, 0xffff0000, v203
	v_pk_add_f32 v[44:45], v[44:45], v[232:233]
	v_pk_add_f32 v[46:47], v[46:47], v[234:235]
	v_pk_add_f32 v[40:41], v[40:41], v[236:237]
	v_pk_add_f32 v[42:43], v[42:43], v[238:239]
	s_waitcnt vmcnt(4)
	v_lshlrev_b32_e32 v232, 16, v204
	v_and_b32_e32 v233, 0xffff0000, v204
	v_lshlrev_b32_e32 v234, 16, v205
	v_and_b32_e32 v235, 0xffff0000, v205
	v_lshlrev_b32_e32 v236, 16, v206
	v_and_b32_e32 v237, 0xffff0000, v206
	v_lshlrev_b32_e32 v238, 16, v207
	v_and_b32_e32 v239, 0xffff0000, v207
	v_pk_add_f32 v[36:37], v[36:37], v[232:233]
	v_pk_add_f32 v[38:39], v[38:39], v[234:235]
	v_pk_add_f32 v[32:33], v[32:33], v[236:237]
	v_pk_add_f32 v[34:35], v[34:35], v[238:239]
	s_waitcnt vmcnt(3)
	v_lshlrev_b32_e32 v232, 16, v208
	v_and_b32_e32 v233, 0xffff0000, v208
	v_lshlrev_b32_e32 v234, 16, v209
	v_and_b32_e32 v235, 0xffff0000, v209
	v_lshlrev_b32_e32 v236, 16, v210
	v_and_b32_e32 v237, 0xffff0000, v210
	v_lshlrev_b32_e32 v238, 16, v211
	v_and_b32_e32 v239, 0xffff0000, v211
	v_pk_add_f32 v[28:29], v[28:29], v[232:233]
	v_pk_add_f32 v[30:31], v[30:31], v[234:235]
	v_pk_add_f32 v[24:25], v[24:25], v[236:237]
	v_pk_add_f32 v[26:27], v[26:27], v[238:239]
	s_waitcnt vmcnt(2)
	v_lshlrev_b32_e32 v232, 16, v212
	v_and_b32_e32 v233, 0xffff0000, v212
	v_lshlrev_b32_e32 v234, 16, v213
	v_and_b32_e32 v235, 0xffff0000, v213
	v_lshlrev_b32_e32 v236, 16, v214
	v_and_b32_e32 v237, 0xffff0000, v214
	v_lshlrev_b32_e32 v238, 16, v215
	v_and_b32_e32 v239, 0xffff0000, v215
	v_pk_add_f32 v[20:21], v[20:21], v[232:233]
	v_pk_add_f32 v[22:23], v[22:23], v[234:235]
	v_pk_add_f32 v[16:17], v[16:17], v[236:237]
	v_pk_add_f32 v[18:19], v[18:19], v[238:239]
	s_waitcnt vmcnt(1)
	v_lshlrev_b32_e32 v232, 16, v216
	v_and_b32_e32 v233, 0xffff0000, v216
	v_lshlrev_b32_e32 v234, 16, v217
	v_and_b32_e32 v235, 0xffff0000, v217
	v_lshlrev_b32_e32 v236, 16, v218
	v_and_b32_e32 v237, 0xffff0000, v218
	v_lshlrev_b32_e32 v238, 16, v219
	v_and_b32_e32 v239, 0xffff0000, v219
	v_pk_add_f32 v[12:13], v[12:13], v[232:233]
	v_pk_add_f32 v[14:15], v[14:15], v[234:235]
	v_pk_add_f32 v[8:9], v[8:9], v[236:237]
	v_pk_add_f32 v[10:11], v[10:11], v[238:239]
	s_waitcnt vmcnt(0)
;     __device__ __forceinline__ void operator()(const f32x4 (&acc)[2][2][4][2], const Unit& u, int wr, int wc, int fr, int fq) const {
;     ...
;                 for (int bj = 0; bj < 2; ++bj) {
;                     f32x4 b0, b1; unpack8(__builtin_nontemporal_load((const u32x4*)(base + off + bj * HALF)), b0, b1);
;                     __builtin_nontemporal_store(b0 + acc[ai][bj][m][0], (f32x4*)(out + off + bj * HALF));
;                     __builtin_nontemporal_store(b1 + acc[ai][bj][m][1], (f32x4*)(out + off + bj * HALF + 4));
;                 }
	v_lshlrev_b32_e32 v232, 16, v220
	v_and_b32_e32 v233, 0xffff0000, v220
	v_lshlrev_b32_e32 v234, 16, v221
	v_and_b32_e32 v235, 0xffff0000, v221
	v_lshlrev_b32_e32 v236, 16, v222
	v_and_b32_e32 v237, 0xffff0000, v222
	v_lshlrev_b32_e32 v238, 16, v223
	v_and_b32_e32 v239, 0xffff0000, v223
	v_pk_add_f32 v[4:5], v[4:5], v[232:233]
	v_pk_add_f32 v[6:7], v[6:7], v[234:235]
	v_pk_add_f32 v[0:1], v[0:1], v[236:237]
	v_pk_add_f32 v[2:3], v[2:3], v[238:239]
	v_mov_b32_e32 v228, v142
	v_ashrrev_i32_e32 v229, 31, v228
	v_lshlrev_b64 v[228:229], 10, v[228:229]
	v_lshl_add_u64 v[228:229], v[228:229], 0, v[140:141]
	v_lshl_add_u64 v[230:231], v[228:229], 2, s[40:41]
	global_store_dwordx4 v[230:231], v[124:127], off nt
	global_store_dwordx4 v[230:231], v[120:123], off offset:16 nt
	global_store_dwordx4 v[230:231], v[116:119], off offset:512 nt
	global_store_dwordx4 v[230:231], v[112:115], off offset:528 nt
	v_or_b32_e32 v228, 16, v142
	v_ashrrev_i32_e32 v229, 31, v228
	v_lshlrev_b64 v[228:229], 10, v[228:229]
	v_lshl_add_u64 v[228:229], v[228:229], 0, v[140:141]
	v_lshl_add_u64 v[230:231], v[228:229], 2, s[40:41]
	global_store_dwordx4 v[230:231], v[108:111], off nt
	global_store_dwordx4 v[230:231], v[104:107], off offset:16 nt
	global_store_dwordx4 v[230:231], v[100:103], off offset:512 nt
	global_store_dwordx4 v[230:231], v[96:99], off offset:528 nt
	v_or_b32_e32 v228, 32, v142
	v_ashrrev_i32_e32 v229, 31, v228
	v_lshlrev_b64 v[228:229], 10, v[228:229]
	v_lshl_add_u64 v[228:229], v[228:229], 0, v[140:141]
	v_lshl_add_u64 v[230:231], v[228:229], 2, s[40:41]
	global_store_dwordx4 v[230:231], v[92:95], off nt
	global_store_dwordx4 v[230:231], v[88:91], off offset:16 nt
	global_store_dwordx4 v[230:231], v[84:87], off offset:512 nt
	global_store_dwordx4 v[230:231], v[80:83], off offset:528 nt
	v_or_b32_e32 v228, 48, v142
	v_ashrrev_i32_e32 v229, 31, v228
	v_lshlrev_b64 v[228:229], 10, v[228:229]
	v_lshl_add_u64 v[228:229], v[228:229], 0, v[140:141]
	v_lshl_add_u64 v[230:231], v[228:229], 2, s[40:41]
	global_store_dwordx4 v[230:231], v[76:79], off nt
	global_store_dwordx4 v[230:231], v[72:75], off offset:16 nt
	global_store_dwordx4 v[230:231], v[68:71], off offset:512 nt
	global_store_dwordx4 v[230:231], v[64:67], off offset:528 nt
	v_add_u32_e32 v228, 0x80, v142
	v_ashrrev_i32_e32 v229, 31, v228
	v_lshlrev_b64 v[228:229], 10, v[228:229]
	v_lshl_add_u64 v[228:229], v[228:229], 0, v[140:141]
	v_lshl_add_u64 v[230:231], v[228:229], 2, s[40:41]
	global_store_dwordx4 v[230:231], v[60:63], off nt
	global_store_dwordx4 v[230:231], v[56:59], off offset:16 nt
	global_store_dwordx4 v[230:231], v[52:55], off offset:512 nt
	global_store_dwordx4 v[230:231], v[48:51], off offset:528 nt
	v_add_u32_e32 v228, 0x90, v142
	v_ashrrev_i32_e32 v229, 31, v228
	v_lshlrev_b64 v[228:229], 10, v[228:229]
	v_lshl_add_u64 v[228:229], v[228:229], 0, v[140:141]
	v_lshl_add_u64 v[230:231], v[228:229], 2, s[40:41]
	global_store_dwordx4 v[230:231], v[44:47], off nt
	global_store_dwordx4 v[230:231], v[40:43], off offset:16 nt
	global_store_dwordx4 v[230:231], v[36:39], off offset:512 nt
	global_store_dwordx4 v[230:231], v[32:35], off offset:528 nt
	v_add_u32_e32 v228, 0xa0, v142
	v_ashrrev_i32_e32 v229, 31, v228
	v_lshlrev_b64 v[228:229], 10, v[228:229]
	v_lshl_add_u64 v[228:229], v[228:229], 0, v[140:141]
	v_lshl_add_u64 v[230:231], v[228:229], 2, s[40:41]
	global_store_dwordx4 v[230:231], v[28:31], off nt
	global_store_dwordx4 v[230:231], v[24:27], off offset:16 nt
	global_store_dwordx4 v[230:231], v[20:23], off offset:512 nt
	global_store_dwordx4 v[230:231], v[16:19], off offset:528 nt
	v_add_u32_e32 v228, 0xb0, v142
	v_ashrrev_i32_e32 v229, 31, v228
	v_lshlrev_b64 v[228:229], 10, v[228:229]
	v_lshl_add_u64 v[228:229], v[228:229], 0, v[140:141]
	v_lshl_add_u64 v[230:231], v[228:229], 2, s[40:41]
	global_store_dwordx4 v[230:231], v[12:15], off nt
	global_store_dwordx4 v[230:231], v[8:11], off offset:16 nt
	global_store_dwordx4 v[230:231], v[4:7], off offset:512 nt
	global_store_dwordx4 v[230:231], v[0:3], off offset:528 nt
	s_cbranch_vccnz .LBB0_2264
	s_andn2_b64 vcc, exec, s[2:3]
	s_cbranch_vccnz .LBB0_2263
	s_barrier
	s_branch .LBB0_2263
